# first two cross-lane reduction steps of the final RMSNorm and of filter_finalize done with v_permlane32_swap / v_permlane16_swap instead of ds_bpermute
# baseline (speedup 1.0000x reference)
; __device__ void filter_finalize_phase() {
;     ...
;     for (int oc = gw; oc < 1024; oc += nw) {
;         const int o = oc >> 9, c = oc & 511;
;         float ns = norms[16384 + lane * 2048 + o * 512 + c] + norms[16384 + lane * 2048 + (2 + o) * 512 + c];
; #pragma unroll
;         for (int sft = 32; sft >= 1; sft >>= 1) ns += __shfl_xor(ns, sft);
;         const float scale = 1.0f / (ns + 1e-6f);
;         const float* kf = hraw + ((size_t)(0 * 2 + o) * 512 + c) * 2048; const float* kb = hraw + ((size_t)(1 * 2 + o) * 512 + c) * 2048;
.LBB0_246:
	v_and_b32_e32 v1, 0xfffffe00, v0
	v_and_b32_e32 v7, 0x1ff, v0
	v_add_u32_e32 v1, v1, v33
	v_or_b32_e32 v34, v1, v7
	v_ashrrev_i32_e32 v36, 9, v0
	v_ashrrev_i32_e32 v35, 31, v34
	v_lshl_add_u64 v[38:39], v[34:35], 2, s[12:13]
	v_add_u32_e32 v34, 2, v36
	v_lshl_add_u32 v1, v34, 9, v33
	v_or_b32_e32 v46, v1, v7
	v_ashrrev_i32_e32 v47, 31, v46
	v_lshl_add_u64 v[46:47], v[46:47], 2, s[12:13]
	global_load_dword v1, v[38:39], off
	global_load_dword v9, v[46:47], off
	v_ashrrev_i32_e32 v37, 31, v36
	v_lshlrev_b64 v[36:37], 22, v[36:37]
	v_lshl_add_u64 v[36:37], s[10:11], 0, v[36:37]
	v_lshlrev_b32_e32 v184, 13, v7
	v_lshl_add_u64 v[36:37], v[36:37], 0, v[184:185]
	v_mov_b32_e32 v38, 0
	s_waitcnt vmcnt(0)
	v_add_f32_e32 v1, v1, v9
	v_mov_b32_e32 v9, v1
	s_nop 1
	v_permlane32_swap_b32 v9, v1
	s_nop 1
	v_add_f32_e32 v1, v1, v9
	v_mov_b32_e32 v9, v1
	s_nop 1
	v_permlane16_swap_b32 v9, v1
	s_nop 1
	v_add_f32_e32 v1, v1, v9
	ds_bpermute_b32 v9, v42, v1
	s_waitcnt lgkmcnt(0)
	v_add_f32_e32 v1, v1, v9
	ds_bpermute_b32 v9, v43, v1
	s_waitcnt lgkmcnt(0)
	v_add_f32_e32 v1, v1, v9
	ds_bpermute_b32 v9, v44, v1
	s_waitcnt lgkmcnt(0)
	v_add_f32_e32 v1, v1, v9
	ds_bpermute_b32 v13, v45, v1
	s_and_saveexec_b64 s[22:23], s[8:9]
	s_cbranch_execz .LBB0_245
	v_mov_b32_e32 v7, v185
	v_lshl_add_u64 v[38:39], v[36:37], 0, v[6:7]
	global_load_dword v38, v[38:39], off
	s_branch .LBB0_245

; __device__ __forceinline__ unsigned cvt_pk_bf16(float lo, float hi) { const f32x2_t v = {lo, hi}; const bf16x2_t b = __builtin_convertvector(v, bf16x2_t); return __builtin_bit_cast(unsigned, b); }
; __device__ void rmsnorm_phase(const float* src, const float* g, float* copy_dst, bf16_t* xn, float* outf) {
;     ...
;     for (int row = gw; row < MT; row += nw) {
;         const f32x4* pr = (const f32x4*)(src + (size_t)row * DM); f32x4 v[4]; float ss = 0.f;
; #pragma unroll
;         for (int j = 0; j < 4; ++j) { v[j] = pr[lane + 64 * j]; ss += v[j][0] * v[j][0] + v[j][1] * v[j][1] + v[j][2] * v[j][2] + v[j][3] * v[j][3]; }
; #pragma unroll
;         for (int o = 32; o >= 1; o >>= 1) ss += __shfl_xor(ss, o);
;         const float r = 1.0f / sqrtf(ss * (1.0f / DM) + 1e-6f);
; #pragma unroll
;         for (int j = 0; j < 4; ++j) { const f32x4 y = v[j] * r * gv[j];
;             if (copy_dst) ((f32x4*)(copy_dst + (size_t)row * DM))[lane + 64 * j] = v[j];
;             if (xn) { u32x2 w; w.x = cvt_pk_bf16(y[0], y[1]); w.y = cvt_pk_bf16(y[2], y[3]); ((u32x2*)(xn + (size_t)row * DM))[lane + 64 * j] = w; }
;             if (outf) ((f32x4*)(outf + (size_t)row * DM))[lane + 64 * j] = y; }
.Lrn_A_go:
	s_andn2_b64 vcc, exec, s[86:87]
	s_waitcnt vmcnt(11)
	v_mul_f32_e32 v33, v29, v29
	s_waitcnt vmcnt(10) lgkmcnt(0)
	v_mul_f32_e32 v42, v25, v25
	s_waitcnt vmcnt(9)
	v_mul_f32_e32 v43, v21, v21
	v_fmac_f32_e32 v33, v28, v28
	v_fmac_f32_e32 v42, v24, v24
	s_waitcnt vmcnt(8)
	v_mul_f32_e32 v44, v17, v17
	v_fmac_f32_e32 v43, v20, v20
	v_fmac_f32_e32 v33, v30, v30
	v_fmac_f32_e32 v42, v26, v26
	v_fmac_f32_e32 v44, v16, v16
	v_fmac_f32_e32 v43, v22, v22
	v_fmac_f32_e32 v33, v31, v31
	v_fmac_f32_e32 v42, v27, v27
	v_fmac_f32_e32 v44, v18, v18
	v_fmac_f32_e32 v43, v23, v23
	v_add_f32_e32 v33, v33, v42
	v_add_f32_e32 v33, v33, v43
	v_fmac_f32_e32 v44, v19, v19
	v_add_f32_e32 v33, v33, v44
	v_mov_b32_e32 v42, v33
	s_nop 1
	v_permlane32_swap_b32 v42, v33
	s_nop 1
	v_add_f32_e32 v33, v33, v42
	v_mov_b32_e32 v42, v33
	s_nop 1
	v_permlane16_swap_b32 v42, v33
	s_nop 1
	v_add_f32_e32 v33, v33, v42
	ds_bpermute_b32 v42, v38, v33
	s_waitcnt lgkmcnt(0)
	v_add_f32_e32 v33, v33, v42
	ds_bpermute_b32 v42, v39, v33
	s_waitcnt lgkmcnt(0)
	v_add_f32_e32 v33, v33, v42
	ds_bpermute_b32 v42, v40, v33
	s_waitcnt lgkmcnt(0)
	v_add_f32_e32 v33, v33, v42
	ds_bpermute_b32 v42, v41, v33
	s_cbranch_vccnz .Lrn_A_lt
	s_waitcnt lgkmcnt(0)
	v_add_f32_e32 v33, v33, v42
	v_fmamk_f32 v33, v33, 0x3a800000, v235
	s_mov_b32 s0, 0xf800000
	v_mul_f32_e32 v42, 0x4f800000, v33
	v_cmp_gt_f32_e32 vcc, s0, v33
	s_nop 1
	v_cndmask_b32_e32 v33, v33, v42, vcc
	v_sqrt_f32_e32 v42, v33
	s_nop 0
	v_add_u32_e32 v43, -1, v42
	v_fma_f32 v45, -v43, v42, v33
	v_add_u32_e32 v44, 1, v42
	v_cmp_ge_f32_e64 s[0:1], 0, v45
	s_nop 1
	v_cndmask_b32_e64 v43, v42, v43, s[0:1]
	v_fma_f32 v42, -v44, v42, v33
	v_cmp_lt_f32_e64 s[0:1], 0, v42
	s_nop 1
	v_cndmask_b32_e64 v42, v43, v44, s[0:1]
	v_mul_f32_e32 v43, 0x37800000, v42
	v_cndmask_b32_e32 v42, v42, v43, vcc
	v_cmp_class_f32_e32 vcc, v33, v236
	s_nop 1
	v_cndmask_b32_e32 v33, v42, v33, vcc
	v_div_scale_f32 v42, s[0:1], v33, v33, 1.0
	v_rcp_f32_e32 v43, v42
	s_nop 0
	v_fma_f32 v44, -v42, v43, 1.0
	v_fmac_f32_e32 v43, v44, v43
	v_div_scale_f32 v44, vcc, 1.0, v33, 1.0
	v_mul_f32_e32 v45, v44, v43
	v_fma_f32 v46, -v42, v45, v44
	v_fmac_f32_e32 v45, v46, v43
	v_fma_f32 v42, -v42, v45, v44
	v_div_fmas_f32 v42, v42, v43, v45
	v_div_fixup_f32 v42, v42, v33, 1.0
	v_pk_mul_f32 v[28:29], v[28:29], v[42:43] op_sel_hi:[1,0]
	v_pk_mul_f32 v[30:31], v[30:31], v[42:43] op_sel_hi:[1,0]
	v_pk_mul_f32 v[24:25], v[24:25], v[42:43] op_sel_hi:[1,0]
	v_pk_mul_f32 v[26:27], v[26:27], v[42:43] op_sel_hi:[1,0]
	v_pk_mul_f32 v[20:21], v[20:21], v[42:43] op_sel_hi:[1,0]
	v_pk_mul_f32 v[22:23], v[22:23], v[42:43] op_sel_hi:[1,0]
	v_pk_mul_f32 v[16:17], v[16:17], v[42:43] op_sel_hi:[1,0]
	v_pk_mul_f32 v[18:19], v[18:19], v[42:43] op_sel_hi:[1,0]
	v_pk_mul_f32 v[30:31], v[2:3], v[30:31]
	v_pk_mul_f32 v[28:29], v[0:1], v[28:29]
	v_pk_mul_f32 v[26:27], v[6:7], v[26:27]
	v_pk_mul_f32 v[24:25], v[4:5], v[24:25]
	v_pk_mul_f32 v[22:23], v[10:11], v[22:23]
	v_pk_mul_f32 v[20:21], v[8:9], v[20:21]
	v_pk_mul_f32 v[18:19], v[14:15], v[18:19]
	v_pk_mul_f32 v[16:17], v[12:13], v[16:17]
	global_store_dwordx4 v[34:35], v[28:31], off offset:-3072
	global_store_dwordx4 v[34:35], v[24:27], off offset:-2048
	global_store_dwordx4 v[34:35], v[20:23], off offset:-1024
	global_store_dwordx4 v[34:35], v[16:19], off

; __device__ __forceinline__ unsigned cvt_pk_bf16(float lo, float hi) { const f32x2_t v = {lo, hi}; const bf16x2_t b = __builtin_convertvector(v, bf16x2_t); return __builtin_bit_cast(unsigned, b); }
; __device__ void rmsnorm_phase(const float* src, const float* g, float* copy_dst, bf16_t* xn, float* outf) {
;     ...
;     for (int row = gw; row < MT; row += nw) {
;         const f32x4* pr = (const f32x4*)(src + (size_t)row * DM); f32x4 v[4]; float ss = 0.f;
; #pragma unroll
;         for (int j = 0; j < 4; ++j) { v[j] = pr[lane + 64 * j]; ss += v[j][0] * v[j][0] + v[j][1] * v[j][1] + v[j][2] * v[j][2] + v[j][3] * v[j][3]; }
; #pragma unroll
;         for (int o = 32; o >= 1; o >>= 1) ss += __shfl_xor(ss, o);
;         const float r = 1.0f / sqrtf(ss * (1.0f / DM) + 1e-6f);
; #pragma unroll
;         for (int j = 0; j < 4; ++j) { const f32x4 y = v[j] * r * gv[j];
;             if (copy_dst) ((f32x4*)(copy_dst + (size_t)row * DM))[lane + 64 * j] = v[j];
;             if (xn) { u32x2 w; w.x = cvt_pk_bf16(y[0], y[1]); w.y = cvt_pk_bf16(y[2], y[3]); ((u32x2*)(xn + (size_t)row * DM))[lane + 64 * j] = w; }
;             if (outf) ((f32x4*)(outf + (size_t)row * DM))[lane + 64 * j] = y; }
.Lrn_B_go:
	s_andn2_b64 vcc, exec, s[86:87]
	s_waitcnt vmcnt(11)
	v_mul_f32_e32 v33, v61, v61
	s_waitcnt vmcnt(10) lgkmcnt(0)
	v_mul_f32_e32 v42, v57, v57
	s_waitcnt vmcnt(9)
	v_mul_f32_e32 v43, v53, v53
	v_fmac_f32_e32 v33, v60, v60
	v_fmac_f32_e32 v42, v56, v56
	s_waitcnt vmcnt(8)
	v_mul_f32_e32 v44, v49, v49
	v_fmac_f32_e32 v43, v52, v52
	v_fmac_f32_e32 v33, v62, v62
	v_fmac_f32_e32 v42, v58, v58
	v_fmac_f32_e32 v44, v48, v48
	v_fmac_f32_e32 v43, v54, v54
	v_fmac_f32_e32 v33, v63, v63
	v_fmac_f32_e32 v42, v59, v59
	v_fmac_f32_e32 v44, v50, v50
	v_fmac_f32_e32 v43, v55, v55
	v_add_f32_e32 v33, v33, v42
	v_add_f32_e32 v33, v33, v43
	v_fmac_f32_e32 v44, v51, v51
	v_add_f32_e32 v33, v33, v44
	v_mov_b32_e32 v42, v33
	s_nop 1
	v_permlane32_swap_b32 v42, v33
	s_nop 1
	v_add_f32_e32 v33, v33, v42
	v_mov_b32_e32 v42, v33
	s_nop 1
	v_permlane16_swap_b32 v42, v33
	s_nop 1
	v_add_f32_e32 v33, v33, v42
	ds_bpermute_b32 v42, v38, v33
	s_waitcnt lgkmcnt(0)
	v_add_f32_e32 v33, v33, v42
	ds_bpermute_b32 v42, v39, v33
	s_waitcnt lgkmcnt(0)
	v_add_f32_e32 v33, v33, v42
	ds_bpermute_b32 v42, v40, v33
	s_waitcnt lgkmcnt(0)
	v_add_f32_e32 v33, v33, v42
	ds_bpermute_b32 v42, v41, v33
	s_cbranch_vccnz .Lrn_B_lt
	s_waitcnt lgkmcnt(0)
	v_add_f32_e32 v33, v33, v42
	v_fmamk_f32 v33, v33, 0x3a800000, v235
	s_mov_b32 s0, 0xf800000
	v_mul_f32_e32 v42, 0x4f800000, v33
	v_cmp_gt_f32_e32 vcc, s0, v33
	s_nop 1
	v_cndmask_b32_e32 v33, v33, v42, vcc
	v_sqrt_f32_e32 v42, v33
	s_nop 0
	v_add_u32_e32 v43, -1, v42
	v_fma_f32 v45, -v43, v42, v33
	v_add_u32_e32 v44, 1, v42
	v_cmp_ge_f32_e64 s[0:1], 0, v45
	s_nop 1
	v_cndmask_b32_e64 v43, v42, v43, s[0:1]
	v_fma_f32 v42, -v44, v42, v33
	v_cmp_lt_f32_e64 s[0:1], 0, v42
	s_nop 1
	v_cndmask_b32_e64 v42, v43, v44, s[0:1]
	v_mul_f32_e32 v43, 0x37800000, v42
	v_cndmask_b32_e32 v42, v42, v43, vcc
	v_cmp_class_f32_e32 vcc, v33, v236
	s_nop 1
	v_cndmask_b32_e32 v33, v42, v33, vcc
	v_div_scale_f32 v42, s[0:1], v33, v33, 1.0
	v_rcp_f32_e32 v43, v42
	s_nop 0
	v_fma_f32 v44, -v42, v43, 1.0
	v_fmac_f32_e32 v43, v44, v43
	v_div_scale_f32 v44, vcc, 1.0, v33, 1.0
	v_mul_f32_e32 v45, v44, v43
	v_fma_f32 v46, -v42, v45, v44
	v_fmac_f32_e32 v45, v46, v43
	v_fma_f32 v42, -v42, v45, v44
	v_div_fmas_f32 v42, v42, v43, v45
	v_div_fixup_f32 v42, v42, v33, 1.0
	v_pk_mul_f32 v[60:61], v[60:61], v[42:43] op_sel_hi:[1,0]
	v_pk_mul_f32 v[62:63], v[62:63], v[42:43] op_sel_hi:[1,0]
	v_pk_mul_f32 v[56:57], v[56:57], v[42:43] op_sel_hi:[1,0]
	v_pk_mul_f32 v[58:59], v[58:59], v[42:43] op_sel_hi:[1,0]
	v_pk_mul_f32 v[52:53], v[52:53], v[42:43] op_sel_hi:[1,0]
	v_pk_mul_f32 v[54:55], v[54:55], v[42:43] op_sel_hi:[1,0]
	v_pk_mul_f32 v[48:49], v[48:49], v[42:43] op_sel_hi:[1,0]
	v_pk_mul_f32 v[50:51], v[50:51], v[42:43] op_sel_hi:[1,0]
	v_pk_mul_f32 v[62:63], v[2:3], v[62:63]
	v_pk_mul_f32 v[60:61], v[0:1], v[60:61]
	v_pk_mul_f32 v[58:59], v[6:7], v[58:59]
	v_pk_mul_f32 v[56:57], v[4:5], v[56:57]
	v_pk_mul_f32 v[54:55], v[10:11], v[54:55]
	v_pk_mul_f32 v[52:53], v[8:9], v[52:53]
	v_pk_mul_f32 v[50:51], v[14:15], v[50:51]
	v_pk_mul_f32 v[48:49], v[12:13], v[48:49]
	global_store_dwordx4 v[34:35], v[60:63], off offset:-3072
	global_store_dwordx4 v[34:35], v[56:59], off offset:-2048
	global_store_dwordx4 v[34:35], v[52:55], off offset:-1024
	global_store_dwordx4 v[34:35], v[48:51], off
